# v24: v20 + hgrn_m1 chunk loop: the v halves are packed at the chunk top so the next chunk's 32 gathers are issued a whole chunk ahead instead of just before the MFMA tail
# speedup vs baseline: 1.0006x; 1.0006x over previous
; #define LAS __attribute__((address_space(3)))
; __device__ __forceinline__ unsigned pk2(float lo, float hi) { return cvt_pk_bf16(lo, hi); }
; #define M1_LOAD(un) do { const int bh_ = (un) >> 6, c_ = (un) & 63; const bf16* prow_ = PROJ + ((size_t)(bh_ >> 2) * SEQ + 64 * c_ + 16 * i) * NPROJ + 128 * (bh_ & 3) + k; \
;         _Pragma("unroll") for (int j = 0; j < 16; ++j) { gr[j] = prow_[(size_t)j * NPROJ + C_HG]; vr[j] = prow_[(size_t)j * NPROJ + C_HV]; } } while (0)
; __device__ __forceinline__ void hgrn_m1(Frame& F) {
;     ...
;             float g[16];
; #pragma unroll
;             for (int j = 0; j < 16; ++j) g[j] = bf2f(gr[j]);
;             float cs[16]; float run = 0.f;
; #pragma unroll
;             for (int j = 0; j < 16; ++j) { run += g[j]; cs[j] = run; }
;             Tl[i * 128 + k] = run;
;             __syncthreads();
;             const float T0 = Tl[k], T1 = Tl[128 + k], T2 = Tl[256 + k], T3 = Tl[384 + k];
;             const float after = (i == 0) ? (T1 + T2 + T3) : (i == 1) ? (T2 + T3) : (i == 2) ? T3 : 0.f;
;             const float Gi = __expf(after);
;             if (i == 0) { const float dc = __expf(T0 + T1 + T2 + T3); dpre *= dc; Dl[k] = dc; }
;             unsigned kw[8], vw[8];
;             float fj[16], e2a[16];
; #pragma unroll
;             for (int j = 0; j < 16; ++j) fj[j] = __expf(g[j]);
;             { float p = Gi;
; #pragma unroll
;               for (int j = 15; j >= 0; --j) { e2a[j] = p; p *= fj[j]; } }
; #pragma unroll
;             for (int j = 0; j < 16; j += 2) {
;                 const float ka = (1.0f - fj[j]) * e2a[j], kb2 = (1.0f - fj[j + 1]) * e2a[j + 1];
;                 kw[j >> 1] = pk2(ka, kb2); vw[j >> 1] = (unsigned)vr[j] | ((unsigned)vr[j + 1] << 16);
;             }
;             *(LAS u32x4*)(KT + k * P64 + 32 * i) = (u32x4){kw[0], kw[1], kw[2], kw[3]}; *(LAS u32x4*)(KT + k * P64 + 32 * i + 16) = (u32x4){kw[4], kw[5], kw[6], kw[7]};
;             *(LAS u32x4*)(VT + k * P64 + 32 * i) = (u32x4){vw[0], vw[1], vw[2], vw[3]}; *(LAS u32x4*)(VT + k * P64 + 32 * i + 16) = (u32x4){vw[4], vw[5], vw[6], vw[7]};
;             { const int nu = (cc < 15) ? unit + 1 : 16 * (rg + F.G); if (nu < 4096) M1_LOAD(nu); }
.LBB0_288:
	s_waitcnt vmcnt(0)
	v_lshlrev_b32_e32 v104, 16, v48
	v_lshlrev_b32_e32 v103, 16, v50
	v_add_f32_e32 v44, 0, v104
	v_lshlrev_b32_e32 v102, 16, v52
	v_add_f32_e32 v44, v44, v103
	v_lshlrev_b32_e32 v101, 16, v54
	v_add_f32_e32 v44, v44, v102
	v_lshlrev_b32_e32 v100, 16, v56
	v_add_f32_e32 v44, v44, v101
	v_lshlrev_b32_e32 v99, 16, v58
	v_add_f32_e32 v44, v44, v100
	v_lshlrev_b32_e32 v98, 16, v60
	v_add_f32_e32 v44, v44, v99
	v_lshlrev_b32_e32 v97, 16, v65
	v_add_f32_e32 v44, v44, v98
	v_lshlrev_b32_e32 v96, 16, v69
	v_add_f32_e32 v44, v44, v97
	v_lshlrev_b32_e32 v95, 16, v71
	v_add_f32_e32 v44, v44, v96
	v_lshlrev_b32_e32 v94, 16, v78
	v_add_f32_e32 v44, v44, v95
	v_lshlrev_b32_e32 v93, 16, v80
	v_add_f32_e32 v44, v44, v94
	v_lshlrev_b32_e32 v92, 16, v82
	v_add_f32_e32 v44, v44, v93
	v_lshlrev_b32_e32 v91, 16, v85
	v_add_f32_e32 v44, v44, v92
	v_lshlrev_b32_e32 v41, 16, v87
	v_add_f32_e32 v44, v44, v91
	v_lshlrev_b32_e32 v43, 16, v89
	v_add_f32_e32 v44, v44, v41
	v_add_f32_e32 v44, v44, v43
	ds_write_b32 v62, v44 offset:36864
	v_lshlrev_b32_e32 v240, 16, v51
	v_lshlrev_b32_e32 v241, 16, v55
	v_lshlrev_b32_e32 v242, 16, v59
	v_lshlrev_b32_e32 v243, 16, v68
	v_lshlrev_b32_e32 v244, 16, v72
	v_lshlrev_b32_e32 v245, 16, v81
	v_lshlrev_b32_e32 v246, 16, v86
	v_lshlrev_b32_e32 v247, 16, v90
	v_or_b32_sdwa v240, v240, v49 dst_sel:DWORD dst_unused:UNUSED_PAD src0_sel:DWORD src1_sel:WORD_0
	v_or_b32_sdwa v241, v241, v53 dst_sel:DWORD dst_unused:UNUSED_PAD src0_sel:DWORD src1_sel:WORD_0
	v_or_b32_sdwa v242, v242, v57 dst_sel:DWORD dst_unused:UNUSED_PAD src0_sel:DWORD src1_sel:WORD_0
	v_or_b32_sdwa v243, v243, v61 dst_sel:DWORD dst_unused:UNUSED_PAD src0_sel:DWORD src1_sel:WORD_0
	v_or_b32_sdwa v244, v244, v70 dst_sel:DWORD dst_unused:UNUSED_PAD src0_sel:DWORD src1_sel:WORD_0
	v_or_b32_sdwa v245, v245, v79 dst_sel:DWORD dst_unused:UNUSED_PAD src0_sel:DWORD src1_sel:WORD_0
	v_or_b32_sdwa v246, v246, v83 dst_sel:DWORD dst_unused:UNUSED_PAD src0_sel:DWORD src1_sel:WORD_0
	v_or_b32_sdwa v247, v247, v88 dst_sel:DWORD dst_unused:UNUSED_PAD src0_sel:DWORD src1_sel:WORD_0
	s_add_i32 s12, s3, s26
	s_cmp_eq_u32 s26, 15
	s_cselect_b32 s12, s11, s12
	s_cmpk_gt_i32 s12, 0xfff
	s_cbranch_scc1 .Lmy_m1_nopf
	s_ashr_i32 s24, s12, 8
	s_ashr_i32 s25, s24, 31
	s_lshl_b32 s13, s12, 6
	s_lshl_b64 s[24:25], s[24:25], 12
	s_and_b32 s13, s13, 0xfc0
	s_or_b32 s24, s24, s13
	v_lshl_add_u64 v[44:45], s[24:25], 0, v[34:35]
	v_mov_b64_e32 v[46:47], s[8:9]
	v_mad_u64_u32 v[46:47], s[24:25], v44, s81, v[46:47]
	s_lshl_b32 s12, s12, 2
	v_mad_i32_i24 v47, v45, s81, v47
	s_and_b32 s16, s12, 0x300
	v_lshl_add_u64 v[44:45], v[46:47], 0, s[16:17]
	v_lshl_add_u64 v[44:45], v[44:45], 0, v[66:67]
	v_add_co_u32_e32 v46, vcc, s87, v44
	s_movk_i32 s12, 0x3000
	s_nop 0
	v_addc_co_u32_e32 v47, vcc, 0, v45, vcc
	global_load_ushort v48, v[44:45], off offset:1024
	global_load_ushort v49, v[44:45], off offset:2048
	global_load_ushort v50, v[46:47], off
	global_load_ushort v51, v[46:47], off offset:1024
	v_add_co_u32_e32 v46, vcc, s12, v44
	s_movk_i32 s12, 0x5000
	s_nop 0
	v_addc_co_u32_e32 v47, vcc, 0, v45, vcc
	global_load_ushort v52, v[46:47], off offset:3072
	v_add_co_u32_e32 v46, vcc, s33, v44
	s_nop 1
	v_addc_co_u32_e32 v47, vcc, 0, v45, vcc
	global_load_ushort v53, v[46:47], off
	v_add_co_u32_e32 v46, vcc, s12, v44
	s_movk_i32 s12, 0x7000
	s_nop 0
	v_addc_co_u32_e32 v47, vcc, 0, v45, vcc
	global_load_ushort v54, v[46:47], off offset:2048
	global_load_ushort v55, v[46:47], off offset:3072
	v_add_co_u32_e32 v46, vcc, s12, v44
	s_mov_b32 s12, 0x9000
	s_nop 0
	v_addc_co_u32_e32 v47, vcc, 0, v45, vcc
	global_load_ushort v56, v[46:47], off offset:1024
	global_load_ushort v57, v[46:47], off offset:2048
	v_add_co_u32_e32 v46, vcc, s12, v44
	s_mov_b32 s12, 0xa000
	s_nop 0
	v_addc_co_u32_e32 v47, vcc, 0, v45, vcc
	global_load_ushort v58, v[46:47], off
	global_load_ushort v59, v[46:47], off offset:1024
	v_add_co_u32_e32 v46, vcc, s12, v44
	s_mov_b32 s12, 0xb000
	s_nop 0
	v_addc_co_u32_e32 v47, vcc, 0, v45, vcc
	global_load_ushort v60, v[46:47], off offset:3072
	v_add_co_u32_e32 v46, vcc, s12, v44
	s_mov_b32 s12, 0xc000
	s_nop 0
	v_addc_co_u32_e32 v47, vcc, 0, v45, vcc
	global_load_ushort v61, v[46:47], off
	v_add_co_u32_e32 v46, vcc, s12, v44
	s_mov_b32 s12, 0xe000
	s_nop 0
	v_addc_co_u32_e32 v47, vcc, 0, v45, vcc
	global_load_ushort v65, v[46:47], off offset:2048
	global_load_ushort v68, v[46:47], off offset:3072
	v_add_co_u32_e32 v46, vcc, s12, v44
	s_mov_b32 s12, 0x11000
	s_nop 0
	v_addc_co_u32_e32 v47, vcc, 0, v45, vcc
	global_load_ushort v69, v[46:47], off offset:1024
	global_load_ushort v70, v[46:47], off offset:2048
	v_add_co_u32_e32 v46, vcc, s64, v44
	s_nop 1
	v_addc_co_u32_e32 v47, vcc, 0, v45, vcc
	global_load_ushort v71, v[46:47], off
	global_load_ushort v72, v[46:47], off offset:1024
	v_add_co_u32_e32 v46, vcc, s12, v44
	s_mov_b32 s12, 0x12000
	s_nop 0
	v_addc_co_u32_e32 v47, vcc, 0, v45, vcc
	global_load_ushort v78, v[46:47], off offset:3072
	v_add_co_u32_e32 v46, vcc, s12, v44
	s_nop 1
	v_addc_co_u32_e32 v47, vcc, 0, v45, vcc
	global_load_ushort v79, v[46:47], off
	v_add_co_u32_e32 v46, vcc, 0x13000, v44
	s_nop 1
	v_addc_co_u32_e32 v47, vcc, 0, v45, vcc
	global_load_ushort v80, v[46:47], off offset:2048
	global_load_ushort v81, v[46:47], off offset:3072
	v_add_co_u32_e32 v46, vcc, 0x15000, v44
	s_nop 1
	v_addc_co_u32_e32 v47, vcc, 0, v45, vcc
	global_load_ushort v82, v[46:47], off offset:1024
	global_load_ushort v83, v[46:47], off offset:2048
	v_add_co_u32_e32 v46, vcc, 0x17000, v44
	s_nop 1
	v_addc_co_u32_e32 v47, vcc, 0, v45, vcc
	global_load_ushort v85, v[46:47], off
	global_load_ushort v86, v[46:47], off offset:1024
	v_add_co_u32_e32 v46, vcc, 0x18000, v44
	s_nop 1
	v_addc_co_u32_e32 v47, vcc, 0, v45, vcc
	global_load_ushort v87, v[46:47], off offset:3072
	v_add_co_u32_e32 v46, vcc, 0x19000, v44
	s_nop 1
	v_addc_co_u32_e32 v47, vcc, 0, v45, vcc
	v_add_co_u32_e32 v44, vcc, 0x1a000, v44
	global_load_ushort v88, v[46:47], off
	s_nop 0
	v_addc_co_u32_e32 v45, vcc, 0, v45, vcc
	global_load_ushort v89, v[44:45], off offset:2048
	global_load_ushort v90, v[44:45], off offset:3072
.Lmy_m1_nopf:
	s_waitcnt lgkmcnt(0)
	s_barrier
	ds_read2st64_b32 v[46:47], v63 offset0:144 offset1:146
	ds_read2st64_b32 v[44:45], v63 offset0:148 offset1:150
	s_and_saveexec_b64 s[12:13], s[38:39]
	s_xor_b64 s[12:13], exec, s[12:13]
	s_cbranch_execz .LBB0_298
	s_and_saveexec_b64 s[24:25], s[40:41]
	s_xor_b64 s[24:25], exec, s[24:25]
	s_cbranch_execz .LBB0_291
	s_waitcnt lgkmcnt(0)
	v_cndmask_b32_e64 v105, 0, v45, s[42:43]

; #define LAS __attribute__((address_space(3)))
; __device__ __forceinline__ unsigned pk2(float lo, float hi) { return cvt_pk_bf16(lo, hi); }
; __device__ __forceinline__ void hgrn_m1(Frame& F) {
;     ...
;             const float T0 = Tl[k], T1 = Tl[128 + k], T2 = Tl[256 + k], T3 = Tl[384 + k];
;             const float after = (i == 0) ? (T1 + T2 + T3) : (i == 1) ? (T2 + T3) : (i == 2) ? T3 : 0.f;
;             const float Gi = __expf(after);
;             if (i == 0) { const float dc = __expf(T0 + T1 + T2 + T3); dpre *= dc; Dl[k] = dc; }
;             unsigned kw[8], vw[8];
;             float fj[16], e2a[16];
; #pragma unroll
;             for (int j = 0; j < 16; ++j) fj[j] = __expf(g[j]);
;             { float p = Gi;
; #pragma unroll
;               for (int j = 15; j >= 0; --j) { e2a[j] = p; p *= fj[j]; } }
; #pragma unroll
;             for (int j = 0; j < 16; j += 2) {
;                 const float ka = (1.0f - fj[j]) * e2a[j], kb2 = (1.0f - fj[j + 1]) * e2a[j + 1];
;                 kw[j >> 1] = pk2(ka, kb2); vw[j >> 1] = (unsigned)vr[j] | ((unsigned)vr[j + 1] << 16);
;             }
;             *(LAS u32x4*)(KT + k * P64 + 32 * i) = (u32x4){kw[0], kw[1], kw[2], kw[3]}; *(LAS u32x4*)(KT + k * P64 + 32 * i + 16) = (u32x4){kw[4], kw[5], kw[6], kw[7]};
;             *(LAS u32x4*)(VT + k * P64 + 32 * i) = (u32x4){vw[0], vw[1], vw[2], vw[3]}; *(LAS u32x4*)(VT + k * P64 + 32 * i + 16) = (u32x4){vw[4], vw[5], vw[6], vw[7]};
.LBB0_296:
	s_or_b64 exec, exec, s[12:13]
	s_waitcnt lgkmcnt(0)
	v_mul_f32_e32 v44, 0x3fb8aa3b, v105
	v_exp_f32_e32 v105, v44
	v_mul_f32_e32 v44, 0x3fb8aa3b, v104
	v_exp_f32_e32 v106, v44
	v_mul_f32_e32 v44, 0x3fb8aa3b, v103
	v_exp_f32_e32 v107, v44
	v_mul_f32_e32 v44, 0x3fb8aa3b, v102
	v_exp_f32_e32 v102, v44
	v_mul_f32_e32 v44, 0x3fb8aa3b, v101
	v_exp_f32_e32 v103, v44
	v_mul_f32_e32 v44, 0x3fb8aa3b, v100
	v_exp_f32_e32 v100, v44
	v_mul_f32_e32 v44, 0x3fb8aa3b, v99
	v_exp_f32_e32 v101, v44
	v_mul_f32_e32 v44, 0x3fb8aa3b, v98
	v_exp_f32_e32 v98, v44
	v_mul_f32_e32 v44, 0x3fb8aa3b, v97
	v_exp_f32_e32 v99, v44
	v_mul_f32_e32 v44, 0x3fb8aa3b, v96
	v_exp_f32_e32 v96, v44
	v_mul_f32_e32 v44, 0x3fb8aa3b, v95
	v_exp_f32_e32 v97, v44
	v_mul_f32_e32 v44, 0x3fb8aa3b, v94
	v_exp_f32_e32 v94, v44
	v_mul_f32_e32 v44, 0x3fb8aa3b, v93
	v_mul_f32_e32 v43, 0x3fb8aa3b, v43
	v_exp_f32_e32 v95, v44
	v_mul_f32_e32 v44, 0x3fb8aa3b, v92
	v_exp_f32_e32 v111, v43
	v_mul_f32_e32 v41, 0x3fb8aa3b, v41
	v_exp_f32_e32 v108, v44
	v_mul_f32_e32 v44, 0x3fb8aa3b, v91
	v_exp_f32_e32 v110, v41
	v_exp_f32_e32 v109, v44
	v_mul_f32_e32 v104, v111, v105
	v_pk_add_f32 v[114:115], v[94:95], 1.0 op_sel_hi:[1,0] neg_lo:[1,0] neg_hi:[1,0]
	v_mul_f32_e32 v113, v110, v104
	v_mul_f32_e32 v112, v109, v113
	v_mul_f32_e32 v117, v108, v112
	v_mul_f32_e32 v116, v95, v117
	v_mul_f32_e32 v95, v94, v116
	v_mul_f32_e32 v94, v97, v95
	v_mul_f32_e32 v123, v96, v94
	v_mul_f32_e32 v122, v99, v123
	v_pk_add_f32 v[120:121], v[98:99], 1.0 op_sel_hi:[1,0] neg_lo:[1,0] neg_hi:[1,0]
	v_mul_f32_e32 v99, v98, v122
	v_mul_f32_e32 v98, v101, v99
	v_pk_add_f32 v[124:125], v[100:101], 1.0 op_sel_hi:[1,0] neg_lo:[1,0] neg_hi:[1,0]
	v_mul_f32_e32 v101, v100, v98
	v_mul_f32_e32 v100, v103, v101
	v_pk_add_f32 v[126:127], v[102:103], 1.0 op_sel_hi:[1,0] neg_lo:[1,0] neg_hi:[1,0]
	v_mul_f32_e32 v103, v102, v100
	v_pk_add_f32 v[118:119], v[96:97], 1.0 op_sel_hi:[1,0] neg_lo:[1,0] neg_hi:[1,0]
	v_pk_add_f32 v[96:97], v[106:107], 1.0 op_sel_hi:[1,0] neg_lo:[1,0] neg_hi:[1,0]
	v_mul_f32_e32 v102, v107, v103
	v_pk_mul_f32 v[96:97], v[96:97], v[102:103]
	v_pk_mul_f32 v[100:101], v[126:127], v[100:101]
	v_cvt_pk_bf16_f32 v96, v96, v97
	v_cvt_pk_bf16_f32 v97, v100, v101
	v_pk_mul_f32 v[98:99], v[124:125], v[98:99]
	v_pk_mul_f32 v[100:101], v[120:121], v[122:123]
	v_pk_mul_f32 v[94:95], v[118:119], v[94:95]
	v_cvt_pk_bf16_f32 v98, v98, v99
	v_cvt_pk_bf16_f32 v99, v100, v101
	v_cvt_pk_bf16_f32 v100, v94, v95
	v_pk_mul_f32 v[94:95], v[114:115], v[116:117]
	v_cvt_pk_bf16_f32 v101, v94, v95
	v_pk_add_f32 v[94:95], v[108:109], 1.0 op_sel_hi:[1,0] neg_lo:[1,0] neg_hi:[1,0]
	v_pk_mul_f32 v[94:95], v[94:95], v[112:113]
	v_cvt_pk_bf16_f32 v102, v94, v95
	v_pk_add_f32 v[106:107], v[110:111], 1.0 op_sel_hi:[1,0] neg_lo:[1,0] neg_hi:[1,0]
	v_pk_mul_f32 v[104:105], v[106:107], v[104:105]
	v_cvt_pk_bf16_f32 v103, v104, v105
	ds_write_b128 v74, v[96:99]
	ds_write_b128 v74, v[100:103] offset:16
	ds_write_b128 v74, v[240:243] offset:18432
	ds_write_b128 v74, v[244:247] offset:18448
	s_branch .LBB0_287
